# v25 + nt hint on P5's once-read f32 residual x tile
# speedup vs baseline: 1.0842x; 1.0059x over previous
; #define LAS __attribute__((address_space(3)))
;     __device__ __forceinline__ void operator()(const pg8::f32x4 (&acc)[2][2][4][2], const Unit& u, int wr, int wc, int fr, int fq) const {
;         const int row0 = u.pm * BM + wr * 64, lane = fr + 16 * fq, rr = lane >> 3, sl = lane & 7;
;         LAS unsigned char* W = scr + (wr * 4 + wc) * 2048;
;         const float* xb = xp + (size_t)(row0 + rr) * DM + (size_t)u.pn * BM + wc * 32 + 4 * sl;
;         bf16* ob = XN + (size_t)(row0 + rr) * DM + (size_t)u.pn * BM + wc * 32 + 4 * sl;
;         pg8::f32x4 xc[2][2], xn[2][2];
; #pragma unroll
;         for (int bj = 0; bj < 2; ++bj)
; #pragma unroll
;             for (int p = 0; p < 2; ++p) xc[bj][p] = *(const pg8::f32x4*)(xb + (size_t)(8 * p) * DM + bj * HALF);
; #pragma unroll
;         for (int g = 0; g < 8; ++g) { const int ai = g >> 2, m = g & 3, rg = ai * HALF + m * 16; float s0 = 0.f, s1 = 0.f;
;             if (g < 7) { const int rgn = ((g + 1) >> 2) * HALF + ((g + 1) & 3) * 16;
; #pragma unroll
;                 for (int bj = 0; bj < 2; ++bj)
; #pragma unroll
;                     for (int p = 0; p < 2; ++p) xn[bj][p] = *(const pg8::f32x4*)(xb + (size_t)(rgn + 8 * p) * DM + bj * HALF); }
; #pragma unroll
;             for (int bj = 0; bj < 2; ++bj) { *(LAS pg8::f32x4*)epi_slot(W, fr, 2 * fq) = acc[ai][bj][m][0]; *(LAS pg8::f32x4*)epi_slot(W, fr, 2 * fq + 1) = acc[ai][bj][m][1];
; #pragma unroll
;                 for (int p = 0; p < 2; ++p) { const pg8::f32x4 x1 = xc[bj][p] + *(const LAS pg8::f32x4*)epi_slot(W, 8 * p + rr, sl);
;                     const float q = (x1[0] * x1[0] + x1[1] * x1[1]) + (x1[2] * x1[2] + x1[3] * x1[3]); if (p == 0) s0 += q; else s1 += q;
;                     v2u w; w.x = cvt_pk_bf16(x1[0], x1[1]); w.y = cvt_pk_bf16(x1[2], x1[3]); *(v2u*)(ob + (size_t)(rg + 8 * p) * DM + bj * HALF) = w; } }
;             s0 += __shfl_xor(s0, 1); s1 += __shfl_xor(s1, 1); s0 += __shfl_xor(s0, 2); s1 += __shfl_xor(s1, 2); s0 += __shfl_xor(s0, 4); s1 += __shfl_xor(s1, 4);
;             if (sl == 0) { __hip_atomic_fetch_add(SS1 + row0 + rg + rr, s0, __ATOMIC_RELAXED, __HIP_MEMORY_SCOPE_AGENT); __hip_atomic_fetch_add(SS1 + row0 + rg + 8 + rr, s1, __ATOMIC_RELAXED, __HIP_MEMORY_SCOPE_AGENT); }
; #pragma unroll
;             for (int bj = 0; bj < 2; ++bj)
; #pragma unroll
;                 for (int p = 0; p < 2; ++p) xc[bj][p] = xn[bj][p]; }
;     }
.LBB0_786:
	s_lshl_b32 s5, s20, 8
	s_add_i32 s38, s5, s58
	v_or_b32_e32 v180, s38, v185
	v_ashrrev_i32_e32 v181, 31, v180
	v_readlane_b32 s76, v238, 4
	v_lshlrev_b64 v[130:131], 12, v[180:181]
	v_readlane_b32 s77, v238, 5
	s_ashr_i32 s5, s4, 31
	s_lshl_b64 s[40:41], s[4:5], 10
	v_lshl_add_u64 v[130:131], s[76:77], 0, v[130:131]
	v_lshl_add_u64 v[130:131], v[130:131], 0, s[40:41]
	s_lshl_b32 s20, s59, 2
	v_lshl_add_u64 v[130:131], v[130:131], 0, s[20:21]
	v_lshlrev_b32_e32 v164, 2, v166
	v_lshl_add_u64 v[178:179], v[130:131], 0, v[164:165]
	global_load_dwordx4 v[142:145], v[178:179], off nt
	v_add_co_u32_e32 v130, vcc, s68, v178
	v_xor_b32_e32 v164, 1, v189
	s_nop 0
	v_addc_co_u32_e32 v131, vcc, 0, v179, vcc
	global_load_dwordx4 v[138:141], v[130:131], off nt
	global_load_dwordx4 v[134:137], v[178:179], off offset:512 nt
	s_nop 0
	global_load_dwordx4 v[130:133], v[130:131], off offset:512 nt
	ds_write_b128 v190, v[126:129]
	ds_write_b128 v191, v[122:125]
	v_and_b32_e32 v122, 64, v189
	v_add_u32_e32 v202, 64, v122
	v_add_co_u32_e32 v122, vcc, s55, v178
	ds_read_b128 v[194:197], v192
	s_nop 0
	v_addc_co_u32_e32 v123, vcc, 0, v179, vcc
	v_add_co_u32_e32 v124, vcc, s63, v178
	v_lshlrev_b64 v[180:181], 11, v[180:181]
	s_nop 0
	v_addc_co_u32_e32 v125, vcc, 0, v179, vcc
	global_load_dwordx4 v[150:153], v[122:123], off nt
	global_load_dwordx4 v[126:129], v[122:123], off offset:512 nt
	global_load_dwordx4 v[146:149], v[124:125], off nt
	s_nop 0
	global_load_dwordx4 v[122:125], v[124:125], off offset:512 nt
	s_lshl_b64 s[4:5], s[4:5], 9
	v_cmp_lt_i32_e32 vcc, v164, v202
	v_lshl_add_u64 v[180:181], s[46:47], 0, v[180:181]
	v_lshl_add_u64 v[180:181], v[180:181], 0, s[4:5]
	v_cndmask_b32_e32 v164, v189, v164, vcc
	s_lshl_b32 s20, s59, 1
	v_lshlrev_b32_e32 v193, 2, v164
	v_lshl_add_u64 v[180:181], v[180:181], 0, s[20:21]
	v_lshlrev_b32_e32 v164, 1, v166
	v_lshl_add_u64 v[180:181], v[180:181], 0, v[164:165]
	s_movk_i32 s29, 0x4000
	v_add_co_u32_e32 v182, vcc, s29, v180
	v_xor_b32_e32 v200, 2, v189
	s_nop 0
	v_addc_co_u32_e32 v183, vcc, 0, v181, vcc
	v_cmp_lt_i32_e32 vcc, v200, v202
	v_xor_b32_e32 v201, 4, v189
	s_ashr_i32 s39, s38, 31
	v_readlane_b32 s78, v238, 6
	v_readlane_b32 s79, v238, 7
	v_readlane_b32 s80, v238, 8
	v_readlane_b32 s81, v238, 9
	v_readlane_b32 s82, v238, 10
	v_readlane_b32 s83, v238, 11
	v_readlane_b32 s84, v238, 12
	v_readlane_b32 s85, v238, 13
	v_readlane_b32 s86, v238, 14
	v_readlane_b32 s87, v238, 15
	v_readlane_b32 s88, v238, 16
	v_readlane_b32 s89, v238, 17
	v_readlane_b32 s90, v238, 18
	v_readlane_b32 s91, v238, 19
	s_waitcnt vmcnt(0) lgkmcnt(0)
	v_pk_add_f32 v[196:197], v[144:145], v[196:197]
	v_pk_add_f32 v[194:195], v[142:143], v[194:195]
	v_mul_f32_e32 v203, v197, v197
	v_cvt_pk_bf16_f32 v198, v194, v195
	v_cvt_pk_bf16_f32 v199, v196, v197
	ds_read_b128 v[142:145], v192 offset:1024
	global_store_dwordx2 v[180:181], v[198:199], off
	v_mul_f32_e32 v164, v195, v195
	v_fmac_f32_e32 v164, v194, v194
	v_fmac_f32_e32 v203, v196, v196
	s_waitcnt lgkmcnt(0)
	v_pk_add_f32 v[140:141], v[140:141], v[144:145]
	v_pk_add_f32 v[138:139], v[138:139], v[142:143]
	v_add_f32_e32 v164, v164, v203
	v_cvt_pk_bf16_f32 v142, v138, v139
	v_cvt_pk_bf16_f32 v143, v140, v141
	ds_write_b128 v190, v[118:121]
	ds_write_b128 v191, v[114:117]
	ds_read_b128 v[114:117], v192
	global_store_dwordx2 v[182:183], v[142:143], off
	v_mul_f32_e32 v144, v139, v139
	v_fmac_f32_e32 v144, v138, v138
	v_mul_f32_e32 v145, v141, v141
	s_waitcnt lgkmcnt(0)
	v_pk_add_f32 v[116:117], v[136:137], v[116:117]
	v_pk_add_f32 v[114:115], v[134:135], v[114:115]
	v_mul_f32_e32 v138, v117, v117
	v_cvt_pk_bf16_f32 v118, v114, v115
	v_cvt_pk_bf16_f32 v119, v116, v117
	ds_read_b128 v[134:137], v192 offset:1024
	v_mul_f32_e32 v121, v115, v115
	v_fmac_f32_e32 v121, v114, v114
	v_fmac_f32_e32 v138, v116, v116
	v_add_f32_e32 v114, v121, v138
	v_add_f32_e32 v121, v164, v114
	s_waitcnt lgkmcnt(0)
	v_pk_add_f32 v[114:115], v[132:133], v[136:137]
	v_pk_add_f32 v[116:117], v[130:131], v[134:135]
	v_mul_f32_e32 v131, v115, v115
	v_mul_f32_e32 v130, v117, v117
	v_fmac_f32_e32 v145, v140, v140
	v_fmac_f32_e32 v130, v116, v116
	v_fmac_f32_e32 v131, v114, v114
	v_add_f32_e32 v120, v144, v145
	v_add_f32_e32 v130, v130, v131
	v_add_f32_e32 v120, v120, v130
	ds_bpermute_b32 v138, v193, v121
	ds_bpermute_b32 v130, v193, v120
	v_cndmask_b32_e32 v131, v189, v200, vcc
	v_lshlrev_b32_e32 v140, 2, v131
	v_cmp_lt_i32_e32 vcc, v201, v202
	s_waitcnt lgkmcnt(1)
	v_add_f32_e32 v121, v121, v138
	s_waitcnt lgkmcnt(0)
	v_add_f32_e32 v120, v120, v130
	ds_bpermute_b32 v131, v140, v121
	ds_bpermute_b32 v130, v140, v120
	v_cndmask_b32_e32 v132, v189, v201, vcc
	v_lshlrev_b32_e32 v141, 2, v132
	global_store_dwordx2 v[180:181], v[118:119], off offset:256
	s_waitcnt lgkmcnt(1)
	v_add_f32_e32 v118, v121, v131
	s_waitcnt lgkmcnt(0)
	v_add_f32_e32 v119, v120, v130
	ds_bpermute_b32 v120, v141, v118
	ds_bpermute_b32 v121, v141, v119
	v_lshl_add_u64 v[138:139], s[38:39], 2, v[168:169]
	v_cvt_pk_bf16_f32 v116, v116, v117
	v_cvt_pk_bf16_f32 v117, v114, v115
	global_store_dwordx2 v[182:183], v[116:117], off offset:256
	s_and_saveexec_b64 s[4:5], s[0:1]
	s_cbranch_execz .LBB0_788
	s_waitcnt lgkmcnt(1)
	v_add_f32_e32 v114, v118, v120
	s_waitcnt lgkmcnt(0)
	v_add_f32_e32 v115, v119, v121
	global_atomic_add_f32 v[138:139], v114, off
	global_atomic_add_f32 v[138:139], v115, off offset:32
; __device__ __forceinline__ unsigned cvt_pk_bf16(float lo, float hi) { unsigned r; asm volatile("v_cvt_pk_bf16_f32 %0, %1, %2" : "=v"(r) : "v"(lo), "v"(hi)); return r; }
; #define LAS __attribute__((address_space(3)))
;     __device__ __forceinline__ void operator()(const pg8::f32x4 (&acc)[2][2][4][2], const Unit& u, int wr, int wc, int fr, int fq) const {
;     ...
;         for (int g = 0; g < 8; ++g) { const int ai = g >> 2, m = g & 3, rg = ai * HALF + m * 16; float s0 = 0.f, s1 = 0.f;
;             if (g < 7) { const int rgn = ((g + 1) >> 2) * HALF + ((g + 1) & 3) * 16;
; #pragma unroll
;                 for (int bj = 0; bj < 2; ++bj)
; #pragma unroll
;                     for (int p = 0; p < 2; ++p) xn[bj][p] = *(const pg8::f32x4*)(xb + (size_t)(rgn + 8 * p) * DM + bj * HALF); }
; #pragma unroll
;             for (int bj = 0; bj < 2; ++bj) { *(LAS pg8::f32x4*)epi_slot(W, fr, 2 * fq) = acc[ai][bj][m][0]; *(LAS pg8::f32x4*)epi_slot(W, fr, 2 * fq + 1) = acc[ai][bj][m][1];
; #pragma unroll
;                 for (int p = 0; p < 2; ++p) { const pg8::f32x4 x1 = xc[bj][p] + *(const LAS pg8::f32x4*)epi_slot(W, 8 * p + rr, sl);
;                     const float q = (x1[0] * x1[0] + x1[1] * x1[1]) + (x1[2] * x1[2] + x1[3] * x1[3]); if (p == 0) s0 += q; else s1 += q;
;                     v2u w; w.x = cvt_pk_bf16(x1[0], x1[1]); w.y = cvt_pk_bf16(x1[2], x1[3]); *(v2u*)(ob + (size_t)(rg + 8 * p) * DM + bj * HALF) = w; } }
;             s0 += __shfl_xor(s0, 1); s1 += __shfl_xor(s1, 1); s0 += __shfl_xor(s0, 2); s1 += __shfl_xor(s1, 2); s0 += __shfl_xor(s0, 4); s1 += __shfl_xor(s1, 4);
;             if (sl == 0) { __hip_atomic_fetch_add(SS1 + row0 + rg + rr, s0, __ATOMIC_RELAXED, __HIP_MEMORY_SCOPE_AGENT); __hip_atomic_fetch_add(SS1 + row0 + rg + 8 + rr, s1, __ATOMIC_RELAXED, __HIP_MEMORY_SCOPE_AGENT); }
; #pragma unroll
;             for (int bj = 0; bj < 2; ++bj)
; #pragma unroll
;                 for (int p = 0; p < 2; ++p) xc[bj][p] = xn[bj][p]; }
.LBB0_788:
	s_or_b64 exec, exec, s[4:5]
	v_add_co_u32_e32 v114, vcc, 0x20000, v178
	s_mov_b32 s4, 0xc000
	s_nop 0
	v_addc_co_u32_e32 v115, vcc, 0, v179, vcc
	v_add_co_u32_e32 v116, vcc, 0x28000, v178
	s_nop 1
	v_addc_co_u32_e32 v117, vcc, 0, v179, vcc
	global_load_dwordx4 v[134:137], v[114:115], off nt
	s_waitcnt lgkmcnt(0)
	global_load_dwordx4 v[118:121], v[114:115], off offset:512 nt
	global_load_dwordx4 v[130:133], v[116:117], off nt
	s_nop 0
	global_load_dwordx4 v[114:117], v[116:117], off offset:512 nt
	ds_write_b128 v190, v[110:113]
	ds_write_b128 v191, v[106:109]
	ds_read_b128 v[106:109], v192
	v_add_co_u32_e32 v112, vcc, s68, v180
	s_waitcnt lgkmcnt(0)
	v_pk_add_f32 v[108:109], v[152:153], v[108:109]
	v_pk_add_f32 v[106:107], v[150:151], v[106:107]
	v_mul_f32_e32 v111, v109, v109
	v_mul_f32_e32 v110, v107, v107
	v_fmac_f32_e32 v110, v106, v106
	v_fmac_f32_e32 v111, v108, v108
	v_add_f32_e32 v142, v110, v111
	v_cvt_pk_bf16_f32 v110, v106, v107
	v_cvt_pk_bf16_f32 v111, v108, v109
	ds_read_b128 v[106:109], v192 offset:1024
	v_addc_co_u32_e32 v113, vcc, 0, v181, vcc
	global_store_dwordx2 v[112:113], v[110:111], off
	s_waitcnt lgkmcnt(0)
	v_pk_add_f32 v[106:107], v[146:147], v[106:107]
	s_nop 0
	v_mul_f32_e32 v110, v107, v107
	v_pk_add_f32 v[108:109], v[148:149], v[108:109]
	v_fmac_f32_e32 v110, v106, v106
	v_cvt_pk_bf16_f32 v106, v106, v107
	v_cvt_pk_bf16_f32 v107, v108, v109
	ds_write_b128 v190, v[102:105]
	ds_write_b128 v191, v[98:101]
	ds_read_b128 v[98:101], v192
	v_mul_f32_e32 v111, v109, v109
	v_add_co_u32_e32 v102, vcc, s4, v180
	v_fmac_f32_e32 v111, v108, v108
	s_waitcnt lgkmcnt(0)
	v_pk_add_f32 v[98:99], v[126:127], v[98:99]
	v_addc_co_u32_e32 v103, vcc, 0, v181, vcc
	v_mul_f32_e32 v108, v99, v99
	global_store_dwordx2 v[102:103], v[106:107], off
	v_pk_add_f32 v[104:105], v[128:129], v[100:101]
	v_fmac_f32_e32 v108, v98, v98
	v_cvt_pk_bf16_f32 v106, v98, v99
	v_cvt_pk_bf16_f32 v107, v104, v105
	ds_read_b128 v[98:101], v192 offset:1024
	v_mul_f32_e32 v105, v105, v105
	v_fmac_f32_e32 v105, v104, v104
	v_add_f32_e32 v104, v108, v105
	v_add_f32_e32 v110, v110, v111
	v_add_f32_e32 v111, v142, v104
	s_waitcnt lgkmcnt(0)
	v_pk_add_f32 v[104:105], v[124:125], v[100:101]
	v_pk_add_f32 v[108:109], v[122:123], v[98:99]
	v_mul_f32_e32 v99, v105, v105
	v_mul_f32_e32 v98, v109, v109
	v_fmac_f32_e32 v98, v108, v108
	v_fmac_f32_e32 v99, v104, v104
	v_add_f32_e32 v98, v98, v99
	v_add_f32_e32 v98, v110, v98
	ds_bpermute_b32 v99, v193, v111
	ds_bpermute_b32 v100, v193, v98
	global_store_dwordx2 v[112:113], v[106:107], off offset:256
	v_cvt_pk_bf16_f32 v106, v108, v109
	v_cvt_pk_bf16_f32 v107, v104, v105
	s_waitcnt lgkmcnt(1)
	v_add_f32_e32 v99, v111, v99
	s_waitcnt lgkmcnt(0)
	v_add_f32_e32 v100, v98, v100
	ds_bpermute_b32 v98, v140, v99
	ds_bpermute_b32 v101, v140, v100
	global_store_dwordx2 v[102:103], v[106:107], off offset:256
	s_waitcnt lgkmcnt(1)
	v_add_f32_e32 v98, v99, v98
	s_waitcnt lgkmcnt(0)
	v_add_f32_e32 v99, v100, v101
	ds_bpermute_b32 v100, v141, v98
	ds_bpermute_b32 v101, v141, v99
	s_and_saveexec_b64 s[4:5], s[0:1]
	s_cbranch_execz .LBB0_790
	s_waitcnt lgkmcnt(1)
	v_add_f32_e32 v98, v98, v100
	s_waitcnt lgkmcnt(0)
	v_add_f32_e32 v99, v99, v101
	global_atomic_add_f32 v[138:139], v98, off offset:64
	global_atomic_add_f32 v[138:139], v99, off offset:96
.LBB0_790:
	s_or_b64 exec, exec, s[4:5]
	v_add_co_u32_e32 v98, vcc, 0x30000, v178
	s_mov_b32 s4, 0x14000
	s_nop 0
	v_addc_co_u32_e32 v99, vcc, 0, v179, vcc
	s_waitcnt lgkmcnt(1)
	v_add_co_u32_e32 v100, vcc, 0x38000, v178
	s_waitcnt lgkmcnt(0)
	s_nop 0
	v_addc_co_u32_e32 v101, vcc, 0, v179, vcc
	global_load_dwordx4 v[110:113], v[98:99], off nt
	global_load_dwordx4 v[102:105], v[98:99], off offset:512 nt
	global_load_dwordx4 v[106:109], v[100:101], off nt
	s_nop 0
	global_load_dwordx4 v[98:101], v[100:101], off offset:512 nt
	ds_write_b128 v190, v[94:97]
	ds_write_b128 v191, v[90:93]
	ds_read_b128 v[90:93], v192
	v_add_co_u32_e32 v96, vcc, s55, v180
	s_waitcnt vmcnt(11) lgkmcnt(0)
	v_pk_add_f32 v[92:93], v[136:137], v[92:93]
	v_pk_add_f32 v[90:91], v[134:135], v[90:91]
	v_mul_f32_e32 v95, v93, v93
	v_mul_f32_e32 v94, v91, v91
	v_fmac_f32_e32 v94, v90, v90
	v_fmac_f32_e32 v95, v92, v92
	v_add_f32_e32 v122, v94, v95
	v_cvt_pk_bf16_f32 v94, v90, v91
	v_cvt_pk_bf16_f32 v95, v92, v93
	ds_read_b128 v[90:93], v192 offset:1024
	v_addc_co_u32_e32 v97, vcc, 0, v181, vcc
	global_store_dwordx2 v[96:97], v[94:95], off
	s_waitcnt vmcnt(10) lgkmcnt(0)
	v_pk_add_f32 v[90:91], v[130:131], v[90:91]
	s_nop 0
	v_mul_f32_e32 v94, v91, v91
	v_pk_add_f32 v[92:93], v[132:133], v[92:93]
	v_fmac_f32_e32 v94, v90, v90
	v_cvt_pk_bf16_f32 v90, v90, v91
	v_cvt_pk_bf16_f32 v91, v92, v93
	ds_write_b128 v190, v[86:89]
	ds_write_b128 v191, v[82:85]
	ds_read_b128 v[82:85], v192
	v_mul_f32_e32 v95, v93, v93
	v_add_co_u32_e32 v86, vcc, s4, v180
	v_fmac_f32_e32 v95, v92, v92
	s_waitcnt lgkmcnt(0)
	v_pk_add_f32 v[82:83], v[118:119], v[82:83]
	v_addc_co_u32_e32 v87, vcc, 0, v181, vcc
	v_mul_f32_e32 v92, v83, v83
	global_store_dwordx2 v[86:87], v[90:91], off
	v_pk_add_f32 v[88:89], v[120:121], v[84:85]
	v_fmac_f32_e32 v92, v82, v82
	v_cvt_pk_bf16_f32 v90, v82, v83
	v_cvt_pk_bf16_f32 v91, v88, v89
	ds_read_b128 v[82:85], v192 offset:1024
	v_mul_f32_e32 v89, v89, v89
	v_fmac_f32_e32 v89, v88, v88
	v_add_f32_e32 v88, v92, v89
	v_add_f32_e32 v94, v94, v95
	v_add_f32_e32 v95, v122, v88
	s_waitcnt vmcnt(10) lgkmcnt(0)
	v_pk_add_f32 v[88:89], v[116:117], v[84:85]
	v_pk_add_f32 v[92:93], v[114:115], v[82:83]
	v_mul_f32_e32 v83, v89, v89
	v_mul_f32_e32 v82, v93, v93
	v_fmac_f32_e32 v82, v92, v92
	v_fmac_f32_e32 v83, v88, v88
	v_add_f32_e32 v82, v82, v83
	v_add_f32_e32 v82, v94, v82
	ds_bpermute_b32 v83, v193, v95
	ds_bpermute_b32 v84, v193, v82
	global_store_dwordx2 v[96:97], v[90:91], off offset:256
	v_cvt_pk_bf16_f32 v90, v92, v93
	v_cvt_pk_bf16_f32 v91, v88, v89
	s_waitcnt lgkmcnt(1)
	v_add_f32_e32 v83, v95, v83
	s_waitcnt lgkmcnt(0)
	v_add_f32_e32 v84, v82, v84
	ds_bpermute_b32 v82, v140, v83
	ds_bpermute_b32 v85, v140, v84
	global_store_dwordx2 v[86:87], v[90:91], off offset:256
	s_waitcnt lgkmcnt(1)
	v_add_f32_e32 v82, v83, v82
	s_waitcnt lgkmcnt(0)
	v_add_f32_e32 v83, v84, v85
	ds_bpermute_b32 v84, v141, v82
	ds_bpermute_b32 v85, v141, v83
	s_and_saveexec_b64 s[4:5], s[0:1]
	s_cbranch_execz .LBB0_792
	s_waitcnt lgkmcnt(1)
	v_add_f32_e32 v82, v82, v84
	s_waitcnt lgkmcnt(0)
	v_add_f32_e32 v83, v83, v85
	global_atomic_add_f32 v[138:139], v82, off offset:128
	global_atomic_add_f32 v[138:139], v83, off offset:160
; __device__ __forceinline__ unsigned cvt_pk_bf16(float lo, float hi) { unsigned r; asm volatile("v_cvt_pk_bf16_f32 %0, %1, %2" : "=v"(r) : "v"(lo), "v"(hi)); return r; }
; #define LAS __attribute__((address_space(3)))
;     __device__ __forceinline__ void operator()(const pg8::f32x4 (&acc)[2][2][4][2], const Unit& u, int wr, int wc, int fr, int fq) const {
;     ...
;         for (int g = 0; g < 8; ++g) { const int ai = g >> 2, m = g & 3, rg = ai * HALF + m * 16; float s0 = 0.f, s1 = 0.f;
;             if (g < 7) { const int rgn = ((g + 1) >> 2) * HALF + ((g + 1) & 3) * 16;
; #pragma unroll
;                 for (int bj = 0; bj < 2; ++bj)
; #pragma unroll
;                     for (int p = 0; p < 2; ++p) xn[bj][p] = *(const pg8::f32x4*)(xb + (size_t)(rgn + 8 * p) * DM + bj * HALF); }
; #pragma unroll
;             for (int bj = 0; bj < 2; ++bj) { *(LAS pg8::f32x4*)epi_slot(W, fr, 2 * fq) = acc[ai][bj][m][0]; *(LAS pg8::f32x4*)epi_slot(W, fr, 2 * fq + 1) = acc[ai][bj][m][1];
; #pragma unroll
;                 for (int p = 0; p < 2; ++p) { const pg8::f32x4 x1 = xc[bj][p] + *(const LAS pg8::f32x4*)epi_slot(W, 8 * p + rr, sl);
;                     const float q = (x1[0] * x1[0] + x1[1] * x1[1]) + (x1[2] * x1[2] + x1[3] * x1[3]); if (p == 0) s0 += q; else s1 += q;
;                     v2u w; w.x = cvt_pk_bf16(x1[0], x1[1]); w.y = cvt_pk_bf16(x1[2], x1[3]); *(v2u*)(ob + (size_t)(rg + 8 * p) * DM + bj * HALF) = w; } }
;             s0 += __shfl_xor(s0, 1); s1 += __shfl_xor(s1, 1); s0 += __shfl_xor(s0, 2); s1 += __shfl_xor(s1, 2); s0 += __shfl_xor(s0, 4); s1 += __shfl_xor(s1, 4);
;             if (sl == 0) { __hip_atomic_fetch_add(SS1 + row0 + rg + rr, s0, __ATOMIC_RELAXED, __HIP_MEMORY_SCOPE_AGENT); __hip_atomic_fetch_add(SS1 + row0 + rg + 8 + rr, s1, __ATOMIC_RELAXED, __HIP_MEMORY_SCOPE_AGENT); }
; #pragma unroll
;             for (int bj = 0; bj < 2; ++bj)
; #pragma unroll
;                 for (int p = 0; p < 2; ++p) xc[bj][p] = xn[bj][p]; }
.LBB0_792:
	s_or_b64 exec, exec, s[4:5]
	v_add_co_u32_e32 v82, vcc, 0x80000, v178
	s_mov_b32 s4, 0x1c000
	s_nop 0
	v_addc_co_u32_e32 v83, vcc, 0, v179, vcc
	s_waitcnt lgkmcnt(1)
	v_add_co_u32_e32 v84, vcc, 0x88000, v178
	s_waitcnt lgkmcnt(0)
	s_nop 0
	v_addc_co_u32_e32 v85, vcc, 0, v179, vcc
	global_load_dwordx4 v[94:97], v[82:83], off nt
	global_load_dwordx4 v[86:89], v[82:83], off offset:512 nt
	global_load_dwordx4 v[90:93], v[84:85], off nt
	s_nop 0
	global_load_dwordx4 v[82:85], v[84:85], off offset:512 nt
	ds_write_b128 v190, v[78:81]
	ds_write_b128 v191, v[74:77]
	ds_read_b128 v[74:77], v192
	v_add_co_u32_e32 v80, vcc, s63, v180
	s_waitcnt vmcnt(11) lgkmcnt(0)
	v_pk_add_f32 v[76:77], v[112:113], v[76:77]
	v_pk_add_f32 v[74:75], v[110:111], v[74:75]
	v_mul_f32_e32 v79, v77, v77
	v_mul_f32_e32 v78, v75, v75
	v_fmac_f32_e32 v78, v74, v74
	v_fmac_f32_e32 v79, v76, v76
	v_add_f32_e32 v110, v78, v79
	v_cvt_pk_bf16_f32 v78, v74, v75
	v_cvt_pk_bf16_f32 v79, v76, v77
	ds_read_b128 v[74:77], v192 offset:1024
	v_addc_co_u32_e32 v81, vcc, 0, v181, vcc
	global_store_dwordx2 v[80:81], v[78:79], off
	s_waitcnt vmcnt(10) lgkmcnt(0)
	v_pk_add_f32 v[74:75], v[106:107], v[74:75]
	s_nop 0
	v_mul_f32_e32 v78, v75, v75
	v_pk_add_f32 v[76:77], v[108:109], v[76:77]
	v_fmac_f32_e32 v78, v74, v74
	v_cvt_pk_bf16_f32 v74, v74, v75
	v_cvt_pk_bf16_f32 v75, v76, v77
	ds_write_b128 v190, v[70:73]
	ds_write_b128 v191, v[66:69]
	ds_read_b128 v[66:69], v192
	v_mul_f32_e32 v79, v77, v77
	v_add_co_u32_e32 v70, vcc, s4, v180
	v_fmac_f32_e32 v79, v76, v76
	s_waitcnt lgkmcnt(0)
	v_pk_add_f32 v[66:67], v[102:103], v[66:67]
	v_addc_co_u32_e32 v71, vcc, 0, v181, vcc
	v_mul_f32_e32 v76, v67, v67
	global_store_dwordx2 v[70:71], v[74:75], off
	v_pk_add_f32 v[72:73], v[104:105], v[68:69]
	v_fmac_f32_e32 v76, v66, v66
	v_cvt_pk_bf16_f32 v74, v66, v67
	v_cvt_pk_bf16_f32 v75, v72, v73
	ds_read_b128 v[66:69], v192 offset:1024
	v_mul_f32_e32 v73, v73, v73
	v_fmac_f32_e32 v73, v72, v72
	v_add_f32_e32 v72, v76, v73
	v_add_f32_e32 v78, v78, v79
	v_add_f32_e32 v79, v110, v72
	s_waitcnt vmcnt(10) lgkmcnt(0)
	v_pk_add_f32 v[72:73], v[100:101], v[68:69]
	v_pk_add_f32 v[76:77], v[98:99], v[66:67]
	v_mul_f32_e32 v67, v73, v73
	v_mul_f32_e32 v66, v77, v77
	v_fmac_f32_e32 v66, v76, v76
	v_fmac_f32_e32 v67, v72, v72
	v_add_f32_e32 v66, v66, v67
	v_add_f32_e32 v66, v78, v66
	ds_bpermute_b32 v67, v193, v79
	ds_bpermute_b32 v68, v193, v66
	global_store_dwordx2 v[80:81], v[74:75], off offset:256
	v_cvt_pk_bf16_f32 v74, v76, v77
	v_cvt_pk_bf16_f32 v75, v72, v73
	s_waitcnt lgkmcnt(1)
	v_add_f32_e32 v67, v79, v67
	s_waitcnt lgkmcnt(0)
	v_add_f32_e32 v68, v66, v68
	ds_bpermute_b32 v66, v140, v67
	ds_bpermute_b32 v69, v140, v68
	global_store_dwordx2 v[70:71], v[74:75], off offset:256
	s_waitcnt lgkmcnt(1)
	v_add_f32_e32 v66, v67, v66
	s_waitcnt lgkmcnt(0)
	v_add_f32_e32 v67, v68, v69
	ds_bpermute_b32 v68, v141, v66
	ds_bpermute_b32 v69, v141, v67
	s_and_saveexec_b64 s[4:5], s[0:1]
	s_cbranch_execz .LBB0_794
	s_waitcnt lgkmcnt(1)
	v_add_f32_e32 v66, v66, v68
	s_waitcnt lgkmcnt(0)
	v_add_f32_e32 v67, v67, v69
	global_atomic_add_f32 v[138:139], v66, off offset:192
	global_atomic_add_f32 v[138:139], v67, off offset:224
.LBB0_794:
	s_or_b64 exec, exec, s[4:5]
	v_add_co_u32_e32 v66, vcc, 0x90000, v178
	s_mov_b32 s4, 0x40000
	s_nop 0
	v_addc_co_u32_e32 v67, vcc, 0, v179, vcc
	s_waitcnt lgkmcnt(1)
	v_add_co_u32_e32 v68, vcc, 0x98000, v178
	s_waitcnt lgkmcnt(0)
	s_nop 0
	v_addc_co_u32_e32 v69, vcc, 0, v179, vcc
	global_load_dwordx4 v[78:81], v[66:67], off nt
	global_load_dwordx4 v[70:73], v[66:67], off offset:512 nt
	global_load_dwordx4 v[74:77], v[68:69], off nt
	s_nop 0
	global_load_dwordx4 v[66:69], v[68:69], off offset:512 nt
	ds_write_b128 v190, v[62:65]
	ds_write_b128 v191, v[58:61]
	ds_read_b128 v[58:61], v192
	v_add_co_u32_e32 v64, vcc, s4, v180
	s_mov_b32 s4, 0x44000
	s_nop 0
	v_addc_co_u32_e32 v65, vcc, 0, v181, vcc
	s_waitcnt vmcnt(11) lgkmcnt(0)
	v_pk_add_f32 v[60:61], v[96:97], v[60:61]
	v_pk_add_f32 v[58:59], v[94:95], v[58:59]
	v_mul_f32_e32 v63, v61, v61
	v_mul_f32_e32 v62, v59, v59
	v_fmac_f32_e32 v62, v58, v58
	v_fmac_f32_e32 v63, v60, v60
	v_add_f32_e32 v94, v62, v63
	v_cvt_pk_bf16_f32 v62, v58, v59
	v_cvt_pk_bf16_f32 v63, v60, v61
	ds_read_b128 v[58:61], v192 offset:1024
	global_store_dwordx2 v[64:65], v[62:63], off
	s_waitcnt vmcnt(10) lgkmcnt(0)
	v_pk_add_f32 v[58:59], v[90:91], v[58:59]
	s_nop 0
	v_mul_f32_e32 v62, v59, v59
	v_pk_add_f32 v[60:61], v[92:93], v[60:61]
	v_fmac_f32_e32 v62, v58, v58
	v_cvt_pk_bf16_f32 v58, v58, v59
	v_cvt_pk_bf16_f32 v59, v60, v61
	ds_write_b128 v190, v[54:57]
	ds_write_b128 v191, v[50:53]
	ds_read_b128 v[50:53], v192
	v_mul_f32_e32 v63, v61, v61
	v_add_co_u32_e32 v54, vcc, s4, v180
	v_fmac_f32_e32 v63, v60, v60
	s_waitcnt lgkmcnt(0)
	v_pk_add_f32 v[50:51], v[86:87], v[50:51]
	v_addc_co_u32_e32 v55, vcc, 0, v181, vcc
	v_mul_f32_e32 v60, v51, v51
	global_store_dwordx2 v[54:55], v[58:59], off
	v_pk_add_f32 v[56:57], v[88:89], v[52:53]
	v_fmac_f32_e32 v60, v50, v50
	v_cvt_pk_bf16_f32 v58, v50, v51
	v_cvt_pk_bf16_f32 v59, v56, v57
	ds_read_b128 v[50:53], v192 offset:1024
	v_mul_f32_e32 v57, v57, v57
	v_fmac_f32_e32 v57, v56, v56
	v_add_f32_e32 v56, v60, v57
	v_add_f32_e32 v62, v62, v63
	v_add_f32_e32 v63, v94, v56
	s_waitcnt vmcnt(10) lgkmcnt(0)
	v_pk_add_f32 v[56:57], v[84:85], v[52:53]
	v_pk_add_f32 v[60:61], v[82:83], v[50:51]
	v_mul_f32_e32 v51, v57, v57
	v_mul_f32_e32 v50, v61, v61
	v_fmac_f32_e32 v50, v60, v60
	v_fmac_f32_e32 v51, v56, v56
	v_add_f32_e32 v50, v50, v51
	v_add_f32_e32 v50, v62, v50
	ds_bpermute_b32 v51, v193, v63
	ds_bpermute_b32 v52, v193, v50
	global_store_dwordx2 v[64:65], v[58:59], off offset:256
	v_cvt_pk_bf16_f32 v58, v60, v61
	v_cvt_pk_bf16_f32 v59, v56, v57
	s_waitcnt lgkmcnt(1)
	v_add_f32_e32 v51, v63, v51
	s_waitcnt lgkmcnt(0)
	v_add_f32_e32 v52, v50, v52
	ds_bpermute_b32 v50, v140, v51
	ds_bpermute_b32 v53, v140, v52
	global_store_dwordx2 v[54:55], v[58:59], off offset:256
	s_waitcnt lgkmcnt(1)
	v_add_f32_e32 v50, v51, v50
	s_waitcnt lgkmcnt(0)
	v_add_f32_e32 v51, v52, v53
	ds_bpermute_b32 v52, v141, v50
	ds_bpermute_b32 v53, v141, v51
	s_and_saveexec_b64 s[4:5], s[0:1]
	s_cbranch_execz .LBB0_796
	s_waitcnt lgkmcnt(1)
	v_add_f32_e32 v50, v50, v52
	s_waitcnt lgkmcnt(0)
	v_add_f32_e32 v51, v51, v53
	global_atomic_add_f32 v[138:139], v50, off offset:512
	global_atomic_add_f32 v[138:139], v51, off offset:544
; __device__ __forceinline__ unsigned cvt_pk_bf16(float lo, float hi) { unsigned r; asm volatile("v_cvt_pk_bf16_f32 %0, %1, %2" : "=v"(r) : "v"(lo), "v"(hi)); return r; }
; #define LAS __attribute__((address_space(3)))
;     __device__ __forceinline__ void operator()(const pg8::f32x4 (&acc)[2][2][4][2], const Unit& u, int wr, int wc, int fr, int fq) const {
;     ...
;         for (int g = 0; g < 8; ++g) { const int ai = g >> 2, m = g & 3, rg = ai * HALF + m * 16; float s0 = 0.f, s1 = 0.f;
;             if (g < 7) { const int rgn = ((g + 1) >> 2) * HALF + ((g + 1) & 3) * 16;
; #pragma unroll
;                 for (int bj = 0; bj < 2; ++bj)
; #pragma unroll
;                     for (int p = 0; p < 2; ++p) xn[bj][p] = *(const pg8::f32x4*)(xb + (size_t)(rgn + 8 * p) * DM + bj * HALF); }
; #pragma unroll
;             for (int bj = 0; bj < 2; ++bj) { *(LAS pg8::f32x4*)epi_slot(W, fr, 2 * fq) = acc[ai][bj][m][0]; *(LAS pg8::f32x4*)epi_slot(W, fr, 2 * fq + 1) = acc[ai][bj][m][1];
; #pragma unroll
;                 for (int p = 0; p < 2; ++p) { const pg8::f32x4 x1 = xc[bj][p] + *(const LAS pg8::f32x4*)epi_slot(W, 8 * p + rr, sl);
;                     const float q = (x1[0] * x1[0] + x1[1] * x1[1]) + (x1[2] * x1[2] + x1[3] * x1[3]); if (p == 0) s0 += q; else s1 += q;
;                     v2u w; w.x = cvt_pk_bf16(x1[0], x1[1]); w.y = cvt_pk_bf16(x1[2], x1[3]); *(v2u*)(ob + (size_t)(rg + 8 * p) * DM + bj * HALF) = w; } }
;             s0 += __shfl_xor(s0, 1); s1 += __shfl_xor(s1, 1); s0 += __shfl_xor(s0, 2); s1 += __shfl_xor(s1, 2); s0 += __shfl_xor(s0, 4); s1 += __shfl_xor(s1, 4);
;             if (sl == 0) { __hip_atomic_fetch_add(SS1 + row0 + rg + rr, s0, __ATOMIC_RELAXED, __HIP_MEMORY_SCOPE_AGENT); __hip_atomic_fetch_add(SS1 + row0 + rg + 8 + rr, s1, __ATOMIC_RELAXED, __HIP_MEMORY_SCOPE_AGENT); }
; #pragma unroll
;             for (int bj = 0; bj < 2; ++bj)
; #pragma unroll
;                 for (int p = 0; p < 2; ++p) xc[bj][p] = xn[bj][p]; }
.LBB0_796:
	s_or_b64 exec, exec, s[4:5]
	v_add_co_u32_e32 v50, vcc, 0xa0000, v178
	s_mov_b32 s4, 0x48000
	s_nop 0
	v_addc_co_u32_e32 v51, vcc, 0, v179, vcc
	s_waitcnt lgkmcnt(1)
	v_add_co_u32_e32 v52, vcc, 0xa8000, v178
	s_waitcnt lgkmcnt(0)
	s_nop 0
	v_addc_co_u32_e32 v53, vcc, 0, v179, vcc
	global_load_dwordx4 v[62:65], v[50:51], off nt
	global_load_dwordx4 v[54:57], v[50:51], off offset:512 nt
	global_load_dwordx4 v[58:61], v[52:53], off nt
	s_nop 0
	global_load_dwordx4 v[50:53], v[52:53], off offset:512 nt
	ds_write_b128 v190, v[46:49]
	ds_write_b128 v191, v[42:45]
	ds_read_b128 v[42:45], v192
	v_add_co_u32_e32 v48, vcc, s4, v180
	s_mov_b32 s4, 0x4c000
	s_nop 0
	v_addc_co_u32_e32 v49, vcc, 0, v181, vcc
	s_waitcnt vmcnt(11) lgkmcnt(0)
	v_pk_add_f32 v[44:45], v[80:81], v[44:45]
	v_pk_add_f32 v[42:43], v[78:79], v[42:43]
	v_mul_f32_e32 v47, v45, v45
	v_mul_f32_e32 v46, v43, v43
	v_fmac_f32_e32 v46, v42, v42
	v_fmac_f32_e32 v47, v44, v44
	v_add_f32_e32 v78, v46, v47
	v_cvt_pk_bf16_f32 v46, v42, v43
	v_cvt_pk_bf16_f32 v47, v44, v45
	ds_read_b128 v[42:45], v192 offset:1024
	global_store_dwordx2 v[48:49], v[46:47], off
	s_waitcnt vmcnt(10) lgkmcnt(0)
	v_pk_add_f32 v[42:43], v[74:75], v[42:43]
	s_nop 0
	v_mul_f32_e32 v46, v43, v43
	v_pk_add_f32 v[44:45], v[76:77], v[44:45]
	v_fmac_f32_e32 v46, v42, v42
	v_cvt_pk_bf16_f32 v42, v42, v43
	v_cvt_pk_bf16_f32 v43, v44, v45
	ds_write_b128 v190, v[38:41]
	ds_write_b128 v191, v[34:37]
	ds_read_b128 v[34:37], v192
	v_mul_f32_e32 v47, v45, v45
	v_add_co_u32_e32 v38, vcc, s4, v180
	v_fmac_f32_e32 v47, v44, v44
	s_waitcnt lgkmcnt(0)
	v_pk_add_f32 v[34:35], v[70:71], v[34:35]
	v_addc_co_u32_e32 v39, vcc, 0, v181, vcc
	v_mul_f32_e32 v44, v35, v35
	global_store_dwordx2 v[38:39], v[42:43], off
	v_pk_add_f32 v[40:41], v[72:73], v[36:37]
	v_fmac_f32_e32 v44, v34, v34
	v_cvt_pk_bf16_f32 v42, v34, v35
	v_cvt_pk_bf16_f32 v43, v40, v41
	ds_read_b128 v[34:37], v192 offset:1024
	v_mul_f32_e32 v41, v41, v41
	v_fmac_f32_e32 v41, v40, v40
	v_add_f32_e32 v40, v44, v41
	v_add_f32_e32 v46, v46, v47
	v_add_f32_e32 v47, v78, v40
	s_waitcnt vmcnt(10) lgkmcnt(0)
	v_pk_add_f32 v[40:41], v[68:69], v[36:37]
	v_pk_add_f32 v[44:45], v[66:67], v[34:35]
	v_mul_f32_e32 v35, v41, v41
	v_mul_f32_e32 v34, v45, v45
	v_fmac_f32_e32 v34, v44, v44
	v_fmac_f32_e32 v35, v40, v40
	v_add_f32_e32 v34, v34, v35
	v_add_f32_e32 v34, v46, v34
	ds_bpermute_b32 v35, v193, v47
	ds_bpermute_b32 v36, v193, v34
	global_store_dwordx2 v[48:49], v[42:43], off offset:256
	v_cvt_pk_bf16_f32 v42, v44, v45
	v_cvt_pk_bf16_f32 v43, v40, v41
	s_waitcnt lgkmcnt(1)
	v_add_f32_e32 v35, v47, v35
	s_waitcnt lgkmcnt(0)
	v_add_f32_e32 v36, v34, v36
	ds_bpermute_b32 v34, v140, v35
	ds_bpermute_b32 v37, v140, v36
	global_store_dwordx2 v[38:39], v[42:43], off offset:256
	s_waitcnt lgkmcnt(1)
	v_add_f32_e32 v34, v35, v34
	s_waitcnt lgkmcnt(0)
	v_add_f32_e32 v35, v36, v37
	ds_bpermute_b32 v36, v141, v34
	ds_bpermute_b32 v37, v141, v35
	s_and_saveexec_b64 s[4:5], s[0:1]
	s_cbranch_execz .LBB0_798
	s_waitcnt lgkmcnt(1)
	v_add_f32_e32 v34, v34, v36
	s_waitcnt lgkmcnt(0)
	v_add_f32_e32 v35, v35, v37
	global_atomic_add_f32 v[138:139], v34, off offset:576
	global_atomic_add_f32 v[138:139], v35, off offset:608
.LBB0_798:
	s_or_b64 exec, exec, s[4:5]
	v_add_co_u32_e32 v34, vcc, 0xb0000, v178
	s_mov_b32 s4, 0x50000
	s_nop 0
	v_addc_co_u32_e32 v35, vcc, 0, v179, vcc
	s_waitcnt lgkmcnt(1)
	v_add_co_u32_e32 v36, vcc, 0xb8000, v178
	s_waitcnt lgkmcnt(0)
	s_nop 0
	v_addc_co_u32_e32 v37, vcc, 0, v179, vcc
	global_load_dwordx4 v[46:49], v[34:35], off nt
	global_load_dwordx4 v[38:41], v[34:35], off offset:512 nt
	global_load_dwordx4 v[42:45], v[36:37], off nt
	s_nop 0
	global_load_dwordx4 v[34:37], v[36:37], off offset:512 nt
	ds_write_b128 v190, v[30:33]
	ds_write_b128 v191, v[26:29]
	ds_read_b128 v[26:29], v192
	v_add_co_u32_e32 v32, vcc, s4, v180
	s_mov_b32 s4, 0x54000
	s_nop 0
	v_addc_co_u32_e32 v33, vcc, 0, v181, vcc
	s_waitcnt vmcnt(11) lgkmcnt(0)
	v_pk_add_f32 v[28:29], v[64:65], v[28:29]
	v_pk_add_f32 v[26:27], v[62:63], v[26:27]
	v_mul_f32_e32 v31, v29, v29
	v_mul_f32_e32 v30, v27, v27
	v_fmac_f32_e32 v30, v26, v26
	v_fmac_f32_e32 v31, v28, v28
	v_add_f32_e32 v62, v30, v31
	v_cvt_pk_bf16_f32 v30, v26, v27
	v_cvt_pk_bf16_f32 v31, v28, v29
	ds_read_b128 v[26:29], v192 offset:1024
	global_store_dwordx2 v[32:33], v[30:31], off
	s_waitcnt vmcnt(10) lgkmcnt(0)
	v_pk_add_f32 v[26:27], v[58:59], v[26:27]
	s_nop 0
	v_mul_f32_e32 v30, v27, v27
	v_pk_add_f32 v[28:29], v[60:61], v[28:29]
	v_fmac_f32_e32 v30, v26, v26
	v_cvt_pk_bf16_f32 v26, v26, v27
	v_cvt_pk_bf16_f32 v27, v28, v29
	ds_write_b128 v190, v[22:25]
	ds_write_b128 v191, v[18:21]
	ds_read_b128 v[18:21], v192
	v_mul_f32_e32 v31, v29, v29
	v_add_co_u32_e32 v22, vcc, s4, v180
	v_fmac_f32_e32 v31, v28, v28
	s_waitcnt lgkmcnt(0)
	v_pk_add_f32 v[18:19], v[54:55], v[18:19]
	v_addc_co_u32_e32 v23, vcc, 0, v181, vcc
	v_mul_f32_e32 v28, v19, v19
	global_store_dwordx2 v[22:23], v[26:27], off
	v_pk_add_f32 v[24:25], v[56:57], v[20:21]
	v_fmac_f32_e32 v28, v18, v18
	v_cvt_pk_bf16_f32 v26, v18, v19
	v_cvt_pk_bf16_f32 v27, v24, v25
	ds_read_b128 v[18:21], v192 offset:1024
	v_mul_f32_e32 v25, v25, v25
	v_fmac_f32_e32 v25, v24, v24
	v_add_f32_e32 v24, v28, v25
	v_add_f32_e32 v30, v30, v31
	v_add_f32_e32 v31, v62, v24
	s_waitcnt vmcnt(10) lgkmcnt(0)
	v_pk_add_f32 v[24:25], v[52:53], v[20:21]
	v_pk_add_f32 v[28:29], v[50:51], v[18:19]
	v_mul_f32_e32 v19, v25, v25
	v_mul_f32_e32 v18, v29, v29
	v_fmac_f32_e32 v18, v28, v28
	v_fmac_f32_e32 v19, v24, v24
	v_add_f32_e32 v18, v18, v19
	v_add_f32_e32 v18, v30, v18
	ds_bpermute_b32 v19, v193, v31
	ds_bpermute_b32 v20, v193, v18
	global_store_dwordx2 v[32:33], v[26:27], off offset:256
	v_cvt_pk_bf16_f32 v26, v28, v29
	v_cvt_pk_bf16_f32 v27, v24, v25
	s_waitcnt lgkmcnt(1)
	v_add_f32_e32 v19, v31, v19
	s_waitcnt lgkmcnt(0)
	v_add_f32_e32 v20, v18, v20
	ds_bpermute_b32 v18, v140, v19
	ds_bpermute_b32 v21, v140, v20
	global_store_dwordx2 v[22:23], v[26:27], off offset:256
	s_waitcnt lgkmcnt(1)
	v_add_f32_e32 v18, v19, v18
	s_waitcnt lgkmcnt(0)
	v_add_f32_e32 v19, v20, v21
	ds_bpermute_b32 v20, v141, v18
	ds_bpermute_b32 v21, v141, v19
	s_and_saveexec_b64 s[4:5], s[0:1]
	s_cbranch_execz .LBB0_800
	s_waitcnt lgkmcnt(1)
	v_add_f32_e32 v18, v18, v20
	s_waitcnt lgkmcnt(0)
	v_add_f32_e32 v19, v19, v21
	global_atomic_add_f32 v[138:139], v18, off offset:640
	global_atomic_add_f32 v[138:139], v19, off offset:672
